# norm1/norm2: adaLN shift/scale loads of a row block issued together (counted vmcnt) instead of 4 serial round trips
# speedup vs baseline: 1.0199x; 1.0199x over previous
.LBB0_638:
	s_or_b64 exec, exec, s[0:1]
	s_waitcnt vmcnt(0)
	v_pk_mul_f32 v[96:97], v[66:67], v[66:67]
	v_pk_mul_f32 v[100:101], v[64:65], v[64:65]
	v_mul_f32_e32 v1, v52, v52
	v_pk_mov_b32 v[102:103], v[100:101], v[96:97] op_sel:[1,0]
	v_mov_b32_e32 v101, v97
	v_pk_add_f32 v[96:97], v[102:103], v[100:101]
	v_pk_mul_f32 v[100:101], v[62:63], v[62:63]
	v_pk_mul_f32 v[102:103], v[60:61], v[60:61]
	v_mul_f32_e32 v87, v53, v53
	s_waitcnt lgkmcnt(1)
	v_pk_mov_b32 v[108:109], v[102:103], v[100:101] op_sel:[1,0]
	v_mov_b32_e32 v103, v101
	v_pk_add_f32 v[100:101], v[108:109], v[102:103]
	v_pk_add_f32 v[96:97], v[96:97], v[96:97] op_sel:[0,1] op_sel_hi:[1,0]
	v_pk_add_f32 v[100:101], v[100:101], v[100:101] op_sel:[0,1] op_sel_hi:[1,0]
	v_mov_b32_e32 v97, v1
	v_mov_b32_e32 v101, v87
	v_mul_f32_e32 v98, v57, v57
	v_mul_f32_e32 v89, v54, v54
	v_pk_add_f32 v[96:97], v[96:97], v[100:101]
	v_pk_fma_f32 v[100:101], v[56:57], v[56:57], v[98:99] op_sel_hi:[1,1,0]
	v_mul_f32_e32 v98, v59, v59
	v_mov_b32_e32 v101, v89
	v_mul_f32_e32 v87, v49, v49
	v_mul_f32_e32 v89, v51, v51
	v_mul_f32_e32 v91, v55, v55
	v_pk_fma_f32 v[102:103], v[58:59], v[58:59], v[98:99] op_sel_hi:[1,1,0]
	v_fmac_f32_e32 v87, v48, v48
	v_fmac_f32_e32 v89, v50, v50
	v_mov_b32_e32 v103, v91
	v_add_f32_e32 v87, v87, v89
	v_mul_f32_e32 v89, v45, v45
	v_mul_f32_e32 v91, v47, v47
	v_fmac_f32_e32 v89, v44, v44
	v_fmac_f32_e32 v91, v46, v46
	v_add_f32_e32 v89, v89, v91
	v_add_f32_e32 v87, v89, v87
	v_mul_f32_e32 v89, v41, v41
	v_mul_f32_e32 v91, v43, v43
	v_fmac_f32_e32 v89, v40, v40
	v_fmac_f32_e32 v91, v42, v42
	v_add_f32_e32 v89, v89, v91
	v_add_f32_e32 v87, v89, v87
	v_mul_f32_e32 v89, v37, v37
	v_mul_f32_e32 v91, v39, v39
	v_fmac_f32_e32 v89, v36, v36
	v_fmac_f32_e32 v91, v38, v38
	v_add_f32_e32 v89, v89, v91
	v_pk_add_f32 v[100:101], v[100:101], v[102:103]
	v_add_f32_e32 v87, v89, v87
	v_mul_f32_e32 v89, v33, v33
	v_mul_f32_e32 v91, v35, v35
	v_pk_add_f32 v[96:97], v[96:97], v[100:101]
	v_fmac_f32_e32 v89, v32, v32
	v_fmac_f32_e32 v91, v34, v34
	v_add_f32_e32 v1, v96, v97
	v_add_f32_e32 v89, v89, v91
	v_mul_f32_e32 v91, v29, v29
	v_mul_f32_e32 v96, v31, v31
	v_fmac_f32_e32 v91, v28, v28
	v_fmac_f32_e32 v96, v30, v30
	v_add_f32_e32 v91, v91, v96
	v_add_f32_e32 v89, v91, v89
	v_mul_f32_e32 v91, v25, v25
	v_mul_f32_e32 v96, v27, v27
	v_fmac_f32_e32 v91, v24, v24
	v_fmac_f32_e32 v96, v26, v26
	v_add_f32_e32 v91, v91, v96
	v_add_f32_e32 v89, v91, v89
	v_mul_f32_e32 v91, v17, v17
	v_mul_f32_e32 v96, v19, v19
	v_fmac_f32_e32 v91, v16, v16
	v_fmac_f32_e32 v96, v18, v18
	v_add_f32_e32 v91, v91, v96
	v_add_f32_e32 v89, v91, v89
	v_mul_f32_e32 v91, v21, v21
	v_mul_f32_e32 v96, v23, v23
	v_fmac_f32_e32 v91, v20, v20
	v_fmac_f32_e32 v96, v22, v22
	v_add_f32_e32 v91, v91, v96
	v_mul_f32_e32 v96, v13, v13
	v_mul_f32_e32 v97, v15, v15
	v_fmac_f32_e32 v96, v12, v12
	v_fmac_f32_e32 v97, v14, v14
	v_add_f32_e32 v96, v96, v97
	v_add_f32_e32 v91, v96, v91
	v_mul_f32_e32 v96, v9, v9
	v_mul_f32_e32 v97, v11, v11
	v_fmac_f32_e32 v96, v8, v8
	v_fmac_f32_e32 v97, v10, v10
	v_add_f32_e32 v96, v96, v97
	v_add_f32_e32 v91, v96, v91
	v_mul_f32_e32 v96, v5, v5
	v_mul_f32_e32 v97, v7, v7
	v_fmac_f32_e32 v96, v4, v4
	v_fmac_f32_e32 v97, v6, v6
	v_add_f32_e32 v96, v96, v97
	v_add_f32_e32 v91, v96, v91
	ds_bpermute_b32 v96, v3, v1
	v_cmp_gt_i32_e64 s[42:43], s29, v0
	s_waitcnt lgkmcnt(0)
	v_add_f32_e32 v1, v1, v96
	ds_bpermute_b32 v96, v3, v87
	s_waitcnt lgkmcnt(0)
	v_add_f32_e32 v87, v87, v96
	ds_bpermute_b32 v96, v3, v89
	s_waitcnt lgkmcnt(0)
	v_add_f32_e32 v89, v89, v96
	ds_bpermute_b32 v96, v3, v91
	s_waitcnt lgkmcnt(0)
	v_add_f32_e32 v91, v91, v96
	ds_bpermute_b32 v96, v69, v1
	s_waitcnt lgkmcnt(0)
	v_add_f32_e32 v1, v1, v96
	ds_bpermute_b32 v96, v69, v87
	s_waitcnt lgkmcnt(0)
	v_add_f32_e32 v87, v87, v96
	ds_bpermute_b32 v96, v69, v89
	s_waitcnt lgkmcnt(0)
	v_add_f32_e32 v89, v89, v96
	ds_bpermute_b32 v96, v69, v91
	s_waitcnt lgkmcnt(0)
	v_add_f32_e32 v91, v91, v96
	ds_bpermute_b32 v96, v99, v1
	s_waitcnt lgkmcnt(0)
	v_add_f32_e32 v1, v1, v96
	ds_bpermute_b32 v96, v99, v87
	s_waitcnt lgkmcnt(0)
	v_add_f32_e32 v87, v87, v96
	ds_bpermute_b32 v96, v99, v89
	s_waitcnt lgkmcnt(0)
	v_add_f32_e32 v89, v89, v96
	ds_bpermute_b32 v96, v99, v91
	s_waitcnt lgkmcnt(0)
	v_add_f32_e32 v91, v91, v96
	ds_bpermute_b32 v96, v104, v1
	s_waitcnt lgkmcnt(0)
	v_add_f32_e32 v1, v1, v96
	ds_bpermute_b32 v96, v104, v87
	s_waitcnt lgkmcnt(0)
	v_add_f32_e32 v87, v87, v96
	ds_bpermute_b32 v96, v104, v89
	s_waitcnt lgkmcnt(0)
	v_add_f32_e32 v89, v89, v96
	ds_bpermute_b32 v96, v104, v91
	s_waitcnt lgkmcnt(0)
	v_add_f32_e32 v91, v91, v96
	ds_bpermute_b32 v96, v105, v1
	s_waitcnt lgkmcnt(0)
	v_add_f32_e32 v96, v1, v96
	ds_bpermute_b32 v1, v105, v87
	s_waitcnt lgkmcnt(0)
	v_add_f32_e32 v111, v87, v1
	ds_bpermute_b32 v87, v106, v96
	ds_bpermute_b32 v1, v105, v89
	ds_bpermute_b32 v112, v106, v111
	s_waitcnt lgkmcnt(2)
	v_add_f32_e32 v87, v96, v87
	v_fmamk_f32 v87, v87, 0x3a800000, v178
	s_waitcnt lgkmcnt(1)
	v_add_f32_e32 v108, v89, v1
	v_cmp_gt_f32_e64 s[0:1], s34, v87
	v_mul_f32_e32 v89, 0x4b800000, v87
	v_mov_b64_e32 v[96:97], s[6:7]
	v_cndmask_b32_e64 v87, v87, v89, s[0:1]
	v_rsq_f32_e32 v87, v87
	ds_bpermute_b32 v1, v105, v91
	ds_bpermute_b32 v109, v106, v108
	v_mul_f32_e32 v89, 0x45800000, v87
	v_cndmask_b32_e64 v98, v87, v89, s[0:1]
	v_ashrrev_i32_e32 v87, 11, v0
	v_add_u32_e32 v89, 0xffffc008, v0
	v_cndmask_b32_e64 v87, v89, v87, s[42:43]
	s_mov_b32 s0, 0x18000
	v_mad_i64_i32 v[102:103], s[0:1], v87, s0, v[96:97]
	s_mov_b64 s[0:1], 0x1000
	s_nop 0
	v_lshl_add_u64 v[100:101], v[102:103], 0, s[0:1]
	v_lshlrev_b32_e32 v96, 2, v68
	v_mov_b32_e32 v97, v2
	v_lshl_add_u64 v[102:103], v[102:103], 0, v[96:97]
	v_lshl_add_u64 v[118:119], v[100:101], 0, v[96:97]
	global_load_dwordx4 v[114:117], v[102:103], off
	v_pk_mul_f32 v[64:65], v[64:65], v[98:99] op_sel_hi:[1,0]
	v_mov_b64_e32 v[214:215], v[118:119]
	global_load_dwordx4 v[118:121], v[118:119], off
	global_load_dwordx4 v[190:193], v[102:103], off offset:1024
	global_load_dwordx4 v[194:197], v[214:215], off offset:1024
	global_load_dwordx4 v[198:201], v[102:103], off offset:2048
	global_load_dwordx4 v[202:205], v[214:215], off offset:2048
	global_load_dwordx4 v[206:209], v[102:103], off offset:3072
	global_load_dwordx4 v[210:213], v[214:215], off offset:3072
	s_mov_b32 s0, 0xbe00000
	v_pk_mul_f32 v[66:67], v[66:67], v[98:99] op_sel_hi:[1,0]
	v_mov_b32_e32 v87, v2
	v_pk_mul_f32 v[60:61], v[60:61], v[98:99] op_sel_hi:[1,0]
	v_pk_mul_f32 v[62:63], v[62:63], v[98:99] op_sel_hi:[1,0]
	v_mov_b32_e32 v89, v2
	v_pk_mul_f32 v[56:57], v[56:57], v[98:99] op_sel_hi:[1,0]
	s_waitcnt lgkmcnt(1)
	v_add_f32_e32 v1, v91, v1
	v_pk_mul_f32 v[58:59], v[58:59], v[98:99] op_sel_hi:[1,0]
	v_mov_b32_e32 v91, v2
	ds_bpermute_b32 v107, v106, v1
	v_pk_mul_f32 v[52:53], v[52:53], v[98:99] op_sel_hi:[1,0]
	v_pk_mul_f32 v[54:55], v[54:55], v[98:99] op_sel_hi:[1,0]
	s_waitcnt vmcnt(6)
	v_pk_add_f32 v[118:119], v[118:119], 1.0 op_sel_hi:[1,0]
	s_nop 0
	v_pk_fma_f32 v[64:65], v[118:119], v[64:65], v[114:115]
	v_pk_add_f32 v[120:121], v[120:121], 1.0 op_sel_hi:[1,0]
	v_cvt_pk_bf16_f32 v114, v64, v65
	v_lshl_add_u64 v[64:65], v[84:85], 0, v[74:75]
	v_add_co_u32_e64 v64, s[0:1], s0, v64
	v_pk_fma_f32 v[66:67], v[120:121], v[66:67], v[116:117]
	s_nop 0
	v_addc_co_u32_e64 v65, s[0:1], 0, v65, s[0:1]
	v_cvt_pk_bf16_f32 v115, v66, v67
	global_store_dwordx2 v[64:65], v[114:115], off
	s_waitcnt vmcnt(5)
	v_pk_add_f32 v[194:195], v[194:195], 1.0 op_sel_hi:[1,0]
	v_pk_add_f32 v[66:67], v[196:197], 1.0 op_sel_hi:[1,0]
	v_pk_fma_f32 v[60:61], v[194:195], v[60:61], v[190:191]
	v_pk_fma_f32 v[62:63], v[66:67], v[62:63], v[192:193]
	v_cvt_pk_bf16_f32 v60, v60, v61
	v_cvt_pk_bf16_f32 v61, v62, v63
	global_store_dwordx2 v[64:65], v[60:61], off offset:512
	s_waitcnt vmcnt(4)
	v_pk_add_f32 v[202:203], v[202:203], 1.0 op_sel_hi:[1,0]
	v_pk_add_f32 v[66:67], v[204:205], 1.0 op_sel_hi:[1,0]
	v_pk_fma_f32 v[56:57], v[56:57], v[202:203], v[198:199]
	v_pk_fma_f32 v[58:59], v[58:59], v[66:67], v[200:201]
	v_cvt_pk_bf16_f32 v56, v56, v57
	v_cvt_pk_bf16_f32 v57, v58, v59
	global_store_dwordx2 v[64:65], v[56:57], off offset:1024
	s_waitcnt vmcnt(3)
	v_pk_add_f32 v[210:211], v[210:211], 1.0 op_sel_hi:[1,0]
	v_pk_add_f32 v[212:213], v[212:213], 1.0 op_sel_hi:[1,0]
	v_pk_fma_f32 v[52:53], v[52:53], v[210:211], v[206:207]
	v_pk_fma_f32 v[54:55], v[54:55], v[212:213], v[208:209]
	v_cvt_pk_bf16_f32 v52, v52, v53
	s_nop 0
	v_cvt_pk_bf16_f32 v53, v54, v55
	global_store_dwordx2 v[64:65], v[52:53], off offset:1536
	s_and_saveexec_b64 s[10:11], s[40:41]
	s_cbranch_execz .LBB0_641
	v_add_f32_e32 v52, v111, v112
	v_fmamk_f32 v52, v52, 0x3a800000, v178
	v_cmp_gt_f32_e64 s[0:1], s34, v52
	v_mul_f32_e32 v53, 0x4b800000, v52
	v_add_u32_e32 v54, 0xffffc008, v110
	v_cndmask_b32_e64 v52, v52, v53, s[0:1]
	v_rsq_f32_e32 v52, v52
	s_nop 0
	v_mul_f32_e32 v53, 0x45800000, v52
	v_cndmask_b32_e64 v52, v52, v53, s[0:1]
	v_cmp_gt_i32_e64 s[0:1], s29, v110
	v_ashrrev_i32_e32 v53, 11, v110
	s_nop 0
	v_cndmask_b32_e64 v53, v54, v53, s[0:1]
	v_mov_b64_e32 v[54:55], s[6:7]
	s_mov_b32 s0, 0x18000
	v_mad_i64_i32 v[56:57], s[0:1], v53, s0, v[54:55]
	s_mov_b64 s[0:1], 0x1000
	s_nop 0
	v_lshl_add_u64 v[54:55], v[56:57], 0, s[0:1]
	v_lshl_add_u64 v[56:57], v[56:57], 0, v[96:97]
	v_lshl_add_u64 v[62:63], v[54:55], 0, v[96:97]
	global_load_dwordx4 v[58:61], v[56:57], off
	v_pk_mul_f32 v[48:49], v[48:49], v[52:53] op_sel_hi:[1,0]
	v_mov_b64_e32 v[214:215], v[62:63]
	global_load_dwordx4 v[62:65], v[62:63], off
	global_load_dwordx4 v[190:193], v[56:57], off offset:1024
	global_load_dwordx4 v[194:197], v[214:215], off offset:1024
	global_load_dwordx4 v[198:201], v[56:57], off offset:2048
	global_load_dwordx4 v[202:205], v[214:215], off offset:2048
	global_load_dwordx4 v[206:209], v[56:57], off offset:3072
	global_load_dwordx4 v[210:213], v[214:215], off offset:3072
	s_mov_b32 s0, 0xbe00000
	v_pk_mul_f32 v[50:51], v[50:51], v[52:53] op_sel_hi:[1,0]
	v_pk_mul_f32 v[44:45], v[44:45], v[52:53] op_sel_hi:[1,0]
	v_pk_mul_f32 v[46:47], v[46:47], v[52:53] op_sel_hi:[1,0]
	v_pk_mul_f32 v[40:41], v[40:41], v[52:53] op_sel_hi:[1,0]
	v_pk_mul_f32 v[42:43], v[42:43], v[52:53] op_sel_hi:[1,0]
	v_pk_mul_f32 v[36:37], v[36:37], v[52:53] op_sel_hi:[1,0]
	v_pk_mul_f32 v[38:39], v[38:39], v[52:53] op_sel_hi:[1,0]
	s_waitcnt vmcnt(6)
	v_pk_add_f32 v[62:63], v[62:63], 1.0 op_sel_hi:[1,0]
	s_nop 0
	v_pk_fma_f32 v[48:49], v[48:49], v[62:63], v[58:59]
	v_pk_add_f32 v[64:65], v[64:65], 1.0 op_sel_hi:[1,0]
	v_cvt_pk_bf16_f32 v58, v48, v49
	v_lshl_add_u64 v[48:49], v[76:77], 0, v[74:75]
	v_add_co_u32_e64 v48, s[0:1], s0, v48
	v_pk_fma_f32 v[50:51], v[50:51], v[64:65], v[60:61]
	s_nop 0
	v_addc_co_u32_e64 v49, s[0:1], 0, v49, s[0:1]
	v_cvt_pk_bf16_f32 v59, v50, v51
	global_store_dwordx2 v[48:49], v[58:59], off
	s_waitcnt vmcnt(5)
	v_pk_add_f32 v[194:195], v[194:195], 1.0 op_sel_hi:[1,0]
	v_pk_add_f32 v[50:51], v[196:197], 1.0 op_sel_hi:[1,0]
	v_pk_fma_f32 v[44:45], v[44:45], v[194:195], v[190:191]
	v_pk_fma_f32 v[46:47], v[46:47], v[50:51], v[192:193]
	v_cvt_pk_bf16_f32 v44, v44, v45
	v_cvt_pk_bf16_f32 v45, v46, v47
	global_store_dwordx2 v[48:49], v[44:45], off offset:512
	s_waitcnt vmcnt(4)
	v_pk_add_f32 v[202:203], v[202:203], 1.0 op_sel_hi:[1,0]
	v_pk_add_f32 v[50:51], v[204:205], 1.0 op_sel_hi:[1,0]
	v_pk_fma_f32 v[40:41], v[40:41], v[202:203], v[198:199]
	v_pk_fma_f32 v[42:43], v[42:43], v[50:51], v[200:201]
	v_cvt_pk_bf16_f32 v40, v40, v41
	v_cvt_pk_bf16_f32 v41, v42, v43
	global_store_dwordx2 v[48:49], v[40:41], off offset:1024
	s_waitcnt vmcnt(3)
	v_pk_add_f32 v[210:211], v[210:211], 1.0 op_sel_hi:[1,0]
	v_pk_add_f32 v[212:213], v[212:213], 1.0 op_sel_hi:[1,0]
	v_pk_fma_f32 v[36:37], v[36:37], v[210:211], v[206:207]
	v_pk_fma_f32 v[38:39], v[38:39], v[212:213], v[208:209]
	v_cvt_pk_bf16_f32 v36, v36, v37
	s_nop 0
	v_cvt_pk_bf16_f32 v37, v38, v39
	global_store_dwordx2 v[48:49], v[36:37], off offset:1536
	s_or_b64 exec, exec, s[10:11]
	s_and_saveexec_b64 s[10:11], s[38:39]
	s_cbranch_execnz .LBB0_642

.LBB0_642:
	s_waitcnt lgkmcnt(1)
	v_add_f32_e32 v36, v108, v109
	v_fmamk_f32 v36, v36, 0x3a800000, v178
	v_cmp_gt_f32_e64 s[0:1], s34, v36
	v_mul_f32_e32 v37, 0x4b800000, v36
	v_add_u32_e32 v38, 0xffffc008, v94
	v_cndmask_b32_e64 v36, v36, v37, s[0:1]
	v_rsq_f32_e32 v36, v36
	v_mov_b32_e32 v97, v2
	v_lshlrev_b64 v[50:51], 11, v[94:95]
	v_mov_b32_e32 v87, v2
	v_mul_f32_e32 v37, 0x45800000, v36
	v_cndmask_b32_e64 v36, v36, v37, s[0:1]
	v_cmp_gt_i32_e64 s[0:1], s29, v94
	v_ashrrev_i32_e32 v37, 11, v94
	v_mov_b32_e32 v89, v2
	v_cndmask_b32_e64 v37, v38, v37, s[0:1]
	v_mov_b64_e32 v[38:39], s[6:7]
	s_mov_b32 s0, 0x18000
	v_mad_i64_i32 v[40:41], s[0:1], v37, s0, v[38:39]
	s_mov_b64 s[0:1], 0x1000
	s_nop 0
	v_lshl_add_u64 v[38:39], v[40:41], 0, s[0:1]
	v_lshl_add_u64 v[40:41], v[40:41], 0, v[96:97]
	v_lshl_add_u64 v[46:47], v[38:39], 0, v[96:97]
	global_load_dwordx4 v[42:45], v[40:41], off
	v_pk_mul_f32 v[32:33], v[32:33], v[36:37] op_sel_hi:[1,0]
	v_mov_b64_e32 v[214:215], v[46:47]
	global_load_dwordx4 v[46:49], v[46:47], off
	global_load_dwordx4 v[190:193], v[40:41], off offset:1024
	global_load_dwordx4 v[194:197], v[214:215], off offset:1024
	global_load_dwordx4 v[198:201], v[40:41], off offset:2048
	global_load_dwordx4 v[202:205], v[214:215], off offset:2048
	global_load_dwordx4 v[206:209], v[40:41], off offset:3072
	global_load_dwordx4 v[210:213], v[214:215], off offset:3072
	v_pk_mul_f32 v[34:35], v[34:35], v[36:37] op_sel_hi:[1,0]
	v_pk_mul_f32 v[28:29], v[28:29], v[36:37] op_sel_hi:[1,0]
	v_pk_mul_f32 v[30:31], v[30:31], v[36:37] op_sel_hi:[1,0]
	v_pk_mul_f32 v[24:25], v[24:25], v[36:37] op_sel_hi:[1,0]
	v_pk_mul_f32 v[26:27], v[26:27], v[36:37] op_sel_hi:[1,0]
	v_mov_b32_e32 v91, v2
	v_pk_mul_f32 v[16:17], v[16:17], v[36:37] op_sel_hi:[1,0]
	v_pk_mul_f32 v[18:19], v[18:19], v[36:37] op_sel_hi:[1,0]
	s_waitcnt vmcnt(6)
	v_pk_add_f32 v[46:47], v[46:47], 1.0 op_sel_hi:[1,0]
	v_pk_add_f32 v[48:49], v[48:49], 1.0 op_sel_hi:[1,0]
	v_pk_fma_f32 v[32:33], v[32:33], v[46:47], v[42:43]
	v_pk_fma_f32 v[34:35], v[34:35], v[48:49], v[44:45]
	v_cvt_pk_bf16_f32 v42, v32, v33
	v_lshl_add_u64 v[32:33], v[72:73], 0, v[50:51]
	v_cvt_pk_bf16_f32 v43, v34, v35
	global_store_dwordx2 v[32:33], v[42:43], off
	s_waitcnt vmcnt(5)
	v_pk_add_f32 v[194:195], v[194:195], 1.0 op_sel_hi:[1,0]
	v_pk_add_f32 v[34:35], v[196:197], 1.0 op_sel_hi:[1,0]
	v_pk_fma_f32 v[28:29], v[28:29], v[194:195], v[190:191]
	v_pk_fma_f32 v[30:31], v[30:31], v[34:35], v[192:193]
	v_cvt_pk_bf16_f32 v28, v28, v29
	v_cvt_pk_bf16_f32 v29, v30, v31
	global_store_dwordx2 v[32:33], v[28:29], off offset:512
	s_waitcnt vmcnt(4)
	v_pk_add_f32 v[202:203], v[202:203], 1.0 op_sel_hi:[1,0]
	v_pk_add_f32 v[34:35], v[204:205], 1.0 op_sel_hi:[1,0]
	v_pk_fma_f32 v[24:25], v[24:25], v[202:203], v[198:199]
	v_pk_fma_f32 v[26:27], v[26:27], v[34:35], v[200:201]
	v_cvt_pk_bf16_f32 v24, v24, v25
	v_cvt_pk_bf16_f32 v25, v26, v27
	global_store_dwordx2 v[32:33], v[24:25], off offset:1024
	s_waitcnt vmcnt(3)
	v_pk_add_f32 v[210:211], v[210:211], 1.0 op_sel_hi:[1,0]
	v_pk_add_f32 v[212:213], v[212:213], 1.0 op_sel_hi:[1,0]
	v_pk_fma_f32 v[16:17], v[16:17], v[210:211], v[206:207]
	v_pk_fma_f32 v[18:19], v[18:19], v[212:213], v[208:209]
	v_cvt_pk_bf16_f32 v16, v16, v17
	s_nop 0
	v_cvt_pk_bf16_f32 v17, v18, v19
	global_store_dwordx2 v[32:33], v[16:17], off offset:1536
	s_or_b64 exec, exec, s[10:11]
	s_and_saveexec_b64 s[0:1], vcc
	s_cbranch_execz .LBB0_631
.LBB0_643:
	s_waitcnt lgkmcnt(0)
	v_add_f32_e32 v1, v1, v107
	v_fmamk_f32 v1, v1, 0x3a800000, v178
	v_cmp_gt_f32_e32 vcc, s34, v1
	v_mul_f32_e32 v16, 0x4b800000, v1
	v_add_u32_e32 v17, 0xffffc008, v92
	v_cndmask_b32_e32 v1, v1, v16, vcc
	v_rsq_f32_e32 v1, v1
	v_mov_b64_e32 v[18:19], s[6:7]
	s_mov_b32 s10, 0x18000
	v_mov_b32_e32 v97, v2
	v_mul_f32_e32 v16, 0x45800000, v1
	v_cndmask_b32_e32 v16, v1, v16, vcc
	v_cmp_gt_i32_e32 vcc, s29, v92
	v_ashrrev_i32_e32 v1, 11, v92
	v_lshlrev_b64 v[36:37], 11, v[92:93]
	v_cndmask_b32_e32 v1, v17, v1, vcc
	v_mad_i64_i32 v[18:19], s[10:11], v1, s10, v[18:19]
	s_mov_b64 s[10:11], 0x1000
	s_nop 0
	v_lshl_add_u64 v[24:25], v[18:19], 0, s[10:11]
	v_lshl_add_u64 v[26:27], v[18:19], 0, v[96:97]
	v_lshl_add_u64 v[18:19], v[24:25], 0, v[96:97]
	global_load_dwordx4 v[28:31], v[26:27], off
	v_mov_b64_e32 v[214:215], v[18:19]
	global_load_dwordx4 v[32:35], v[18:19], off
	global_load_dwordx4 v[190:193], v[26:27], off offset:1024
	global_load_dwordx4 v[194:197], v[214:215], off offset:1024
	global_load_dwordx4 v[198:201], v[26:27], off offset:2048
	global_load_dwordx4 v[202:205], v[214:215], off offset:2048
	global_load_dwordx4 v[206:209], v[26:27], off offset:3072
	global_load_dwordx4 v[210:213], v[214:215], off offset:3072
	v_pk_mul_f32 v[18:19], v[20:21], v[16:17] op_sel_hi:[1,0]
	v_pk_mul_f32 v[20:21], v[22:23], v[16:17] op_sel_hi:[1,0]
	v_mov_b32_e32 v87, v2
	v_pk_mul_f32 v[12:13], v[12:13], v[16:17] op_sel_hi:[1,0]
	v_pk_mul_f32 v[14:15], v[14:15], v[16:17] op_sel_hi:[1,0]
	v_mov_b32_e32 v89, v2
	v_pk_mul_f32 v[8:9], v[8:9], v[16:17] op_sel_hi:[1,0]
	v_pk_mul_f32 v[10:11], v[10:11], v[16:17] op_sel_hi:[1,0]
	v_mov_b32_e32 v91, v2
	v_pk_mul_f32 v[4:5], v[4:5], v[16:17] op_sel_hi:[1,0]
	v_pk_mul_f32 v[6:7], v[6:7], v[16:17] op_sel_hi:[1,0]
	s_waitcnt vmcnt(6)
	v_pk_add_f32 v[32:33], v[32:33], 1.0 op_sel_hi:[1,0]
	v_pk_add_f32 v[22:23], v[34:35], 1.0 op_sel_hi:[1,0]
	v_pk_fma_f32 v[18:19], v[18:19], v[32:33], v[28:29]
	v_pk_fma_f32 v[20:21], v[20:21], v[22:23], v[30:31]
	v_cvt_pk_bf16_f32 v22, v18, v19
	v_lshl_add_u64 v[18:19], v[72:73], 0, v[36:37]
	v_cvt_pk_bf16_f32 v23, v20, v21
	global_store_dwordx2 v[18:19], v[22:23], off
	s_waitcnt vmcnt(5)
	v_pk_add_f32 v[194:195], v[194:195], 1.0 op_sel_hi:[1,0]
	v_pk_add_f32 v[196:197], v[196:197], 1.0 op_sel_hi:[1,0]
	v_pk_fma_f32 v[12:13], v[12:13], v[194:195], v[190:191]
	v_pk_fma_f32 v[14:15], v[14:15], v[196:197], v[192:193]
	v_cvt_pk_bf16_f32 v12, v12, v13
	v_cvt_pk_bf16_f32 v13, v14, v15
	global_store_dwordx2 v[18:19], v[12:13], off offset:512
	s_waitcnt vmcnt(4)
	v_pk_add_f32 v[202:203], v[202:203], 1.0 op_sel_hi:[1,0]
	v_pk_add_f32 v[204:205], v[204:205], 1.0 op_sel_hi:[1,0]
	v_pk_fma_f32 v[8:9], v[8:9], v[202:203], v[198:199]
	v_pk_fma_f32 v[10:11], v[10:11], v[204:205], v[200:201]
	v_cvt_pk_bf16_f32 v8, v8, v9
	v_cvt_pk_bf16_f32 v9, v10, v11
	global_store_dwordx2 v[18:19], v[8:9], off offset:1024
	s_waitcnt vmcnt(3)
	v_pk_add_f32 v[210:211], v[210:211], 1.0 op_sel_hi:[1,0]
	v_pk_add_f32 v[212:213], v[212:213], 1.0 op_sel_hi:[1,0]
	v_pk_fma_f32 v[4:5], v[4:5], v[210:211], v[206:207]
	v_pk_fma_f32 v[6:7], v[6:7], v[212:213], v[208:209]
	v_cvt_pk_bf16_f32 v4, v4, v5
	s_nop 0
	v_cvt_pk_bf16_f32 v5, v6, v7
	global_store_dwordx2 v[18:19], v[4:5], off offset:1536
	s_branch .LBB0_631

.LBB0_746:
	s_or_b64 exec, exec, s[10:11]
	s_waitcnt vmcnt(0) lgkmcnt(0)
	v_pk_mul_f32 v[98:99], v[66:67], v[66:67]
	v_pk_mul_f32 v[100:101], v[64:65], v[64:65]
	v_mul_f32_e32 v73, v52, v52
	v_pk_mov_b32 v[106:107], v[100:101], v[98:99] op_sel:[1,0]
	v_mov_b32_e32 v101, v99
	v_pk_add_f32 v[98:99], v[106:107], v[100:101]
	v_pk_mul_f32 v[100:101], v[62:63], v[62:63]
	v_pk_mul_f32 v[106:107], v[60:61], v[60:61]
	v_mul_f32_e32 v79, v53, v53
	v_pk_mov_b32 v[108:109], v[106:107], v[100:101] op_sel:[1,0]
	v_mov_b32_e32 v107, v101
	v_pk_add_f32 v[100:101], v[108:109], v[106:107]
	v_pk_add_f32 v[98:99], v[98:99], v[98:99] op_sel:[0,1] op_sel_hi:[1,0]
	v_pk_add_f32 v[100:101], v[100:101], v[100:101] op_sel:[0,1] op_sel_hi:[1,0]
	v_mov_b32_e32 v99, v73
	v_mov_b32_e32 v101, v79
	v_mul_f32_e32 v96, v57, v57
	v_mul_f32_e32 v81, v54, v54
	v_pk_add_f32 v[98:99], v[98:99], v[100:101]
	v_pk_fma_f32 v[100:101], v[56:57], v[56:57], v[96:97] op_sel_hi:[1,1,0]
	v_mul_f32_e32 v96, v59, v59
	v_mov_b32_e32 v101, v81
	v_mul_f32_e32 v79, v49, v49
	v_mul_f32_e32 v81, v51, v51
	v_mul_f32_e32 v83, v55, v55
	v_pk_fma_f32 v[106:107], v[58:59], v[58:59], v[96:97] op_sel_hi:[1,1,0]
	v_fmac_f32_e32 v79, v48, v48
	v_fmac_f32_e32 v81, v50, v50
	v_mov_b32_e32 v107, v83
	v_add_f32_e32 v79, v79, v81
	v_mul_f32_e32 v81, v45, v45
	v_mul_f32_e32 v83, v47, v47
	v_fmac_f32_e32 v81, v44, v44
	v_fmac_f32_e32 v83, v46, v46
	v_add_f32_e32 v81, v81, v83
	v_add_f32_e32 v79, v81, v79
	v_mul_f32_e32 v81, v41, v41
	v_mul_f32_e32 v83, v43, v43
	v_fmac_f32_e32 v81, v40, v40
	v_fmac_f32_e32 v83, v42, v42
	v_add_f32_e32 v81, v81, v83
	v_add_f32_e32 v79, v81, v79
	v_mul_f32_e32 v81, v33, v33
	v_mul_f32_e32 v83, v35, v35
	v_fmac_f32_e32 v81, v32, v32
	v_fmac_f32_e32 v83, v34, v34
	v_add_f32_e32 v81, v81, v83
	v_add_f32_e32 v79, v81, v79
	v_mul_f32_e32 v81, v37, v37
	v_mul_f32_e32 v83, v39, v39
	v_fmac_f32_e32 v81, v36, v36
	v_fmac_f32_e32 v83, v38, v38
	v_add_f32_e32 v81, v81, v83
	v_mul_f32_e32 v83, v29, v29
	v_mul_f32_e32 v85, v31, v31
	v_fmac_f32_e32 v83, v28, v28
	v_fmac_f32_e32 v85, v30, v30
	v_add_f32_e32 v83, v83, v85
	v_add_f32_e32 v81, v83, v81
	v_mul_f32_e32 v83, v25, v25
	v_mul_f32_e32 v85, v27, v27
	v_fmac_f32_e32 v83, v24, v24
	v_fmac_f32_e32 v85, v26, v26
	v_add_f32_e32 v83, v83, v85
	v_add_f32_e32 v81, v83, v81
	v_mul_f32_e32 v83, v17, v17
	v_mul_f32_e32 v85, v19, v19
	v_fmac_f32_e32 v83, v16, v16
	v_fmac_f32_e32 v85, v18, v18
	v_add_f32_e32 v83, v83, v85
	v_add_f32_e32 v81, v83, v81
	v_mul_f32_e32 v83, v21, v21
	v_mul_f32_e32 v85, v23, v23
	v_fmac_f32_e32 v83, v20, v20
	v_fmac_f32_e32 v85, v22, v22
	v_add_f32_e32 v83, v83, v85
	v_mul_f32_e32 v85, v13, v13
	v_mul_f32_e32 v87, v15, v15
	v_fmac_f32_e32 v85, v12, v12
	v_fmac_f32_e32 v87, v14, v14
	v_add_f32_e32 v85, v85, v87
	v_add_f32_e32 v83, v85, v83
	v_mul_f32_e32 v85, v9, v9
	v_mul_f32_e32 v87, v11, v11
	v_fmac_f32_e32 v85, v8, v8
	v_fmac_f32_e32 v87, v10, v10
	v_add_f32_e32 v85, v85, v87
	v_pk_add_f32 v[100:101], v[100:101], v[106:107]
	v_add_f32_e32 v83, v85, v83
	v_mul_f32_e32 v85, v5, v5
	v_mul_f32_e32 v87, v7, v7
	v_pk_add_f32 v[98:99], v[98:99], v[100:101]
	v_fmac_f32_e32 v85, v4, v4
	v_fmac_f32_e32 v87, v6, v6
	v_add_f32_e32 v73, v98, v99
	v_add_f32_e32 v85, v85, v87
	v_add_f32_e32 v83, v85, v83
	ds_bpermute_b32 v85, v3, v73
	v_mov_b64_e32 v[98:99], s[8:9]
	s_mov_b32 s10, 0x18000
	s_waitcnt lgkmcnt(0)
	v_add_f32_e32 v73, v73, v85
	ds_bpermute_b32 v85, v3, v79
	s_waitcnt lgkmcnt(0)
	v_add_f32_e32 v79, v79, v85
	ds_bpermute_b32 v85, v3, v81
	s_waitcnt lgkmcnt(0)
	v_add_f32_e32 v81, v81, v85
	ds_bpermute_b32 v85, v3, v83
	s_waitcnt lgkmcnt(0)
	v_add_f32_e32 v83, v83, v85
	ds_bpermute_b32 v85, v69, v73
	s_waitcnt lgkmcnt(0)
	v_add_f32_e32 v73, v73, v85
	ds_bpermute_b32 v85, v69, v79
	s_waitcnt lgkmcnt(0)
	v_add_f32_e32 v79, v79, v85
	ds_bpermute_b32 v85, v69, v81
	s_waitcnt lgkmcnt(0)
	v_add_f32_e32 v81, v81, v85
	ds_bpermute_b32 v85, v69, v83
	s_waitcnt lgkmcnt(0)
	v_add_f32_e32 v83, v83, v85
	ds_bpermute_b32 v85, v97, v73
	s_waitcnt lgkmcnt(0)
	v_add_f32_e32 v73, v73, v85
	ds_bpermute_b32 v85, v97, v79
	s_waitcnt lgkmcnt(0)
	v_add_f32_e32 v79, v79, v85
	ds_bpermute_b32 v85, v97, v81
	s_waitcnt lgkmcnt(0)
	v_add_f32_e32 v81, v81, v85
	ds_bpermute_b32 v85, v97, v83
	s_waitcnt lgkmcnt(0)
	v_add_f32_e32 v83, v83, v85
	ds_bpermute_b32 v85, v102, v73
	s_waitcnt lgkmcnt(0)
	v_add_f32_e32 v73, v73, v85
	ds_bpermute_b32 v85, v102, v79
	s_waitcnt lgkmcnt(0)
	v_add_f32_e32 v79, v79, v85
	ds_bpermute_b32 v85, v102, v81
	s_waitcnt lgkmcnt(0)
	v_add_f32_e32 v81, v81, v85
	ds_bpermute_b32 v85, v102, v83
	s_waitcnt lgkmcnt(0)
	v_add_f32_e32 v83, v83, v85
	ds_bpermute_b32 v85, v103, v73
	s_waitcnt lgkmcnt(0)
	v_add_f32_e32 v95, v73, v85
	ds_bpermute_b32 v73, v103, v79
	s_waitcnt lgkmcnt(0)
	v_add_f32_e32 v91, v79, v73
	ds_bpermute_b32 v79, v104, v95
	ds_bpermute_b32 v73, v103, v81
	ds_bpermute_b32 v93, v104, v91
	s_waitcnt lgkmcnt(2)
	v_add_f32_e32 v79, v95, v79
	v_fmamk_f32 v79, v79, 0x3a800000, v178
	s_waitcnt lgkmcnt(1)
	v_add_f32_e32 v87, v81, v73
	v_cmp_gt_f32_e32 vcc, s34, v79
	v_mul_f32_e32 v81, 0x4b800000, v79
	ds_bpermute_b32 v73, v103, v83
	v_cndmask_b32_e32 v79, v79, v81, vcc
	v_rsq_f32_e32 v79, v79
	ds_bpermute_b32 v89, v104, v87
	s_waitcnt lgkmcnt(1)
	v_add_f32_e32 v73, v83, v73
	v_mul_f32_e32 v81, 0x45800000, v79
	v_cndmask_b32_e32 v96, v79, v81, vcc
	v_cmp_gt_i32_e32 vcc, s29, v77
	v_ashrrev_i32_e32 v77, 11, v77
	v_add_u32_e32 v79, 8, v72
	v_cndmask_b32_e32 v77, v79, v77, vcc
	v_mad_i64_i32 v[100:101], s[10:11], v77, s10, v[98:99]
	s_mov_b64 s[10:11], 0x1000
	s_nop 0
	v_lshl_add_u64 v[98:99], v[100:101], 0, s[10:11]
	v_mov_b32_e32 v83, v2
	v_lshl_add_u64 v[100:101], v[100:101], 0, v[82:83]
	v_lshl_add_u64 v[110:111], v[98:99], 0, v[82:83]
	global_load_dwordx4 v[106:109], v[100:101], off
	v_pk_mul_f32 v[64:65], v[64:65], v[96:97] op_sel_hi:[1,0]
	v_mov_b64_e32 v[214:215], v[110:111]
	global_load_dwordx4 v[110:113], v[110:111], off
	global_load_dwordx4 v[190:193], v[100:101], off offset:1024
	global_load_dwordx4 v[194:197], v[214:215], off offset:1024
	global_load_dwordx4 v[198:201], v[100:101], off offset:2048
	global_load_dwordx4 v[202:205], v[214:215], off offset:2048
	global_load_dwordx4 v[206:209], v[100:101], off offset:3072
	global_load_dwordx4 v[210:213], v[214:215], off offset:3072
	v_pk_mul_f32 v[66:67], v[66:67], v[96:97] op_sel_hi:[1,0]
	v_mov_b32_e32 v77, v2
	v_pk_mul_f32 v[60:61], v[60:61], v[96:97] op_sel_hi:[1,0]
	v_pk_mul_f32 v[62:63], v[62:63], v[96:97] op_sel_hi:[1,0]
	v_mov_b32_e32 v79, v2
	v_pk_mul_f32 v[56:57], v[56:57], v[96:97] op_sel_hi:[1,0]
	v_pk_mul_f32 v[58:59], v[58:59], v[96:97] op_sel_hi:[1,0]
	v_mov_b32_e32 v81, v2
	ds_bpermute_b32 v85, v104, v73
	v_pk_mul_f32 v[52:53], v[52:53], v[96:97] op_sel_hi:[1,0]
	v_pk_mul_f32 v[54:55], v[54:55], v[96:97] op_sel_hi:[1,0]
	s_waitcnt vmcnt(6)
	v_pk_add_f32 v[110:111], v[110:111], 1.0 op_sel_hi:[1,0]
	v_pk_add_f32 v[112:113], v[112:113], 1.0 op_sel_hi:[1,0]
	v_pk_fma_f32 v[64:65], v[110:111], v[64:65], v[106:107]
	v_pk_fma_f32 v[66:67], v[112:113], v[66:67], v[108:109]
	v_cvt_pk_bf16_f32 v64, v64, v65
	v_cvt_pk_bf16_f32 v65, v66, v67
	global_store_dwordx2 v[74:75], v[64:65], off
	s_waitcnt vmcnt(5)
	v_pk_add_f32 v[194:195], v[194:195], 1.0 op_sel_hi:[1,0]
	v_pk_add_f32 v[196:197], v[196:197], 1.0 op_sel_hi:[1,0]
	v_pk_fma_f32 v[60:61], v[194:195], v[60:61], v[190:191]
	v_pk_fma_f32 v[62:63], v[196:197], v[62:63], v[192:193]
	v_cvt_pk_bf16_f32 v60, v60, v61
	v_cvt_pk_bf16_f32 v61, v62, v63
	global_store_dwordx2 v[74:75], v[60:61], off offset:512
	s_waitcnt vmcnt(4)
	v_pk_add_f32 v[202:203], v[202:203], 1.0 op_sel_hi:[1,0]
	v_pk_add_f32 v[204:205], v[204:205], 1.0 op_sel_hi:[1,0]
	v_pk_fma_f32 v[56:57], v[56:57], v[202:203], v[198:199]
	v_pk_fma_f32 v[58:59], v[58:59], v[204:205], v[200:201]
	v_cvt_pk_bf16_f32 v56, v56, v57
	v_cvt_pk_bf16_f32 v57, v58, v59
	global_store_dwordx2 v[74:75], v[56:57], off offset:1024
	s_waitcnt vmcnt(3)
	v_pk_add_f32 v[210:211], v[210:211], 1.0 op_sel_hi:[1,0]
	v_pk_add_f32 v[212:213], v[212:213], 1.0 op_sel_hi:[1,0]
	v_pk_fma_f32 v[52:53], v[52:53], v[210:211], v[206:207]
	v_pk_fma_f32 v[54:55], v[54:55], v[212:213], v[208:209]
	v_cvt_pk_bf16_f32 v52, v52, v53
	s_nop 0
	v_cvt_pk_bf16_f32 v53, v54, v55
	global_store_dwordx2 v[74:75], v[52:53], off offset:1536
	s_and_saveexec_b64 s[10:11], s[42:43]
	s_cbranch_execz .LBB0_749
	v_add_f32_e32 v52, v91, v93
	v_fmamk_f32 v52, v52, 0x3a800000, v178
	v_cmp_gt_f32_e32 vcc, s34, v52
	v_mul_f32_e32 v53, 0x4b800000, v52
	v_add_u32_e32 v54, 8, v94
	v_cndmask_b32_e32 v52, v52, v53, vcc
	v_rsq_f32_e32 v52, v52
	s_mov_b32 s12, 0x18000
	v_ashrrev_i32_e32 v93, 31, v92
	v_lshlrev_b64 v[66:67], 11, v[92:93]
	v_mul_f32_e32 v53, 0x45800000, v52
	v_cndmask_b32_e32 v52, v52, v53, vcc
	v_cmp_gt_i32_e32 vcc, s29, v92
	v_ashrrev_i32_e32 v53, 11, v92
	s_nop 0
	v_cndmask_b32_e32 v53, v54, v53, vcc
	v_mov_b64_e32 v[54:55], s[8:9]
	v_mad_i64_i32 v[56:57], s[12:13], v53, s12, v[54:55]
	s_mov_b64 s[12:13], 0x1000
	s_nop 0
	v_lshl_add_u64 v[54:55], v[56:57], 0, s[12:13]
	v_lshl_add_u64 v[56:57], v[56:57], 0, v[82:83]
	v_lshl_add_u64 v[62:63], v[54:55], 0, v[82:83]
	global_load_dwordx4 v[58:61], v[56:57], off
	v_pk_mul_f32 v[48:49], v[48:49], v[52:53] op_sel_hi:[1,0]
	v_mov_b64_e32 v[214:215], v[62:63]
	global_load_dwordx4 v[62:65], v[62:63], off
	global_load_dwordx4 v[190:193], v[56:57], off offset:1024
	global_load_dwordx4 v[194:197], v[214:215], off offset:1024
	global_load_dwordx4 v[198:201], v[56:57], off offset:2048
	global_load_dwordx4 v[202:205], v[214:215], off offset:2048
	global_load_dwordx4 v[206:209], v[56:57], off offset:3072
	global_load_dwordx4 v[210:213], v[214:215], off offset:3072
	v_pk_mul_f32 v[50:51], v[50:51], v[52:53] op_sel_hi:[1,0]
	v_pk_mul_f32 v[44:45], v[44:45], v[52:53] op_sel_hi:[1,0]
	v_pk_mul_f32 v[46:47], v[46:47], v[52:53] op_sel_hi:[1,0]
	v_pk_mul_f32 v[40:41], v[40:41], v[52:53] op_sel_hi:[1,0]
	v_pk_mul_f32 v[42:43], v[42:43], v[52:53] op_sel_hi:[1,0]
	v_pk_mul_f32 v[32:33], v[32:33], v[52:53] op_sel_hi:[1,0]
	v_pk_mul_f32 v[34:35], v[34:35], v[52:53] op_sel_hi:[1,0]
	s_waitcnt vmcnt(6)
	v_pk_add_f32 v[62:63], v[62:63], 1.0 op_sel_hi:[1,0]
	v_pk_add_f32 v[64:65], v[64:65], 1.0 op_sel_hi:[1,0]
	v_pk_fma_f32 v[48:49], v[48:49], v[62:63], v[58:59]
	v_pk_fma_f32 v[50:51], v[50:51], v[64:65], v[60:61]
	v_cvt_pk_bf16_f32 v58, v48, v49
	v_lshl_add_u64 v[48:49], v[70:71], 0, v[66:67]
	v_cvt_pk_bf16_f32 v59, v50, v51
	global_store_dwordx2 v[48:49], v[58:59], off
	s_waitcnt vmcnt(5)
	v_pk_add_f32 v[194:195], v[194:195], 1.0 op_sel_hi:[1,0]
	v_pk_add_f32 v[50:51], v[196:197], 1.0 op_sel_hi:[1,0]
	v_pk_fma_f32 v[44:45], v[44:45], v[194:195], v[190:191]
	v_pk_fma_f32 v[46:47], v[46:47], v[50:51], v[192:193]
	v_cvt_pk_bf16_f32 v44, v44, v45
	v_cvt_pk_bf16_f32 v45, v46, v47
	global_store_dwordx2 v[48:49], v[44:45], off offset:512
	s_waitcnt vmcnt(4)
	v_pk_add_f32 v[202:203], v[202:203], 1.0 op_sel_hi:[1,0]
	v_pk_add_f32 v[50:51], v[204:205], 1.0 op_sel_hi:[1,0]
	v_pk_fma_f32 v[40:41], v[40:41], v[202:203], v[198:199]
	v_pk_fma_f32 v[42:43], v[42:43], v[50:51], v[200:201]
	v_cvt_pk_bf16_f32 v40, v40, v41
	v_cvt_pk_bf16_f32 v41, v42, v43
	global_store_dwordx2 v[48:49], v[40:41], off offset:1024
	s_waitcnt vmcnt(3)
	v_pk_add_f32 v[210:211], v[210:211], 1.0 op_sel_hi:[1,0]
	v_pk_add_f32 v[212:213], v[212:213], 1.0 op_sel_hi:[1,0]
	v_pk_fma_f32 v[32:33], v[32:33], v[210:211], v[206:207]
	v_pk_fma_f32 v[34:35], v[34:35], v[212:213], v[208:209]
	v_cvt_pk_bf16_f32 v32, v32, v33
	s_nop 0
	v_cvt_pk_bf16_f32 v33, v34, v35
	global_store_dwordx2 v[48:49], v[32:33], off offset:1536
	s_or_b64 exec, exec, s[10:11]
	s_and_saveexec_b64 s[10:11], s[40:41]
	s_cbranch_execnz .LBB0_750

.LBB0_750:
	s_waitcnt lgkmcnt(1)
	v_add_f32_e32 v32, v87, v89
	v_fmamk_f32 v32, v32, 0x3a800000, v178
	v_cmp_gt_f32_e32 vcc, s34, v32
	v_mul_f32_e32 v33, 0x4b800000, v32
	v_add_u32_e32 v34, 8, v90
	v_cndmask_b32_e32 v32, v32, v33, vcc
	v_rsq_f32_e32 v32, v32
	s_mov_b32 s12, 0x18000
	v_mov_b32_e32 v83, v2
	v_ashrrev_i32_e32 v89, 31, v88
	v_mul_f32_e32 v33, 0x45800000, v32
	v_cndmask_b32_e32 v32, v32, v33, vcc
	v_cmp_gt_i32_e32 vcc, s29, v88
	v_ashrrev_i32_e32 v33, 11, v88
	v_lshlrev_b64 v[52:53], 11, v[88:89]
	v_cndmask_b32_e32 v33, v34, v33, vcc
	v_mov_b64_e32 v[34:35], s[8:9]
	v_mad_i64_i32 v[34:35], s[12:13], v33, s12, v[34:35]
	s_mov_b64 s[12:13], 0x1000
	s_nop 0
	v_lshl_add_u64 v[40:41], v[34:35], 0, s[12:13]
	v_lshl_add_u64 v[42:43], v[34:35], 0, v[82:83]
	v_lshl_add_u64 v[34:35], v[40:41], 0, v[82:83]
	global_load_dwordx4 v[44:47], v[42:43], off
	v_mov_b64_e32 v[214:215], v[34:35]
	global_load_dwordx4 v[48:51], v[34:35], off
	global_load_dwordx4 v[190:193], v[42:43], off offset:1024
	global_load_dwordx4 v[194:197], v[214:215], off offset:1024
	global_load_dwordx4 v[198:201], v[42:43], off offset:2048
	global_load_dwordx4 v[202:205], v[214:215], off offset:2048
	global_load_dwordx4 v[206:209], v[42:43], off offset:3072
	global_load_dwordx4 v[210:213], v[214:215], off offset:3072
	v_pk_mul_f32 v[34:35], v[36:37], v[32:33] op_sel_hi:[1,0]
	v_pk_mul_f32 v[36:37], v[38:39], v[32:33] op_sel_hi:[1,0]
	v_mov_b32_e32 v77, v2
	v_pk_mul_f32 v[28:29], v[28:29], v[32:33] op_sel_hi:[1,0]
	v_pk_mul_f32 v[30:31], v[30:31], v[32:33] op_sel_hi:[1,0]
	v_mov_b32_e32 v79, v2
	v_pk_mul_f32 v[24:25], v[24:25], v[32:33] op_sel_hi:[1,0]
	v_pk_mul_f32 v[26:27], v[26:27], v[32:33] op_sel_hi:[1,0]
	v_mov_b32_e32 v81, v2
	v_pk_mul_f32 v[16:17], v[16:17], v[32:33] op_sel_hi:[1,0]
	v_pk_mul_f32 v[18:19], v[18:19], v[32:33] op_sel_hi:[1,0]
	s_waitcnt vmcnt(6)
	v_pk_add_f32 v[48:49], v[48:49], 1.0 op_sel_hi:[1,0]
	v_pk_add_f32 v[38:39], v[50:51], 1.0 op_sel_hi:[1,0]
	v_pk_fma_f32 v[34:35], v[34:35], v[48:49], v[44:45]
	v_pk_fma_f32 v[36:37], v[36:37], v[38:39], v[46:47]
	v_cvt_pk_bf16_f32 v38, v34, v35
	v_lshl_add_u64 v[34:35], v[70:71], 0, v[52:53]
	v_cvt_pk_bf16_f32 v39, v36, v37
	global_store_dwordx2 v[34:35], v[38:39], off
	s_waitcnt vmcnt(5)
	v_pk_add_f32 v[194:195], v[194:195], 1.0 op_sel_hi:[1,0]
	v_pk_add_f32 v[196:197], v[196:197], 1.0 op_sel_hi:[1,0]
	v_pk_fma_f32 v[28:29], v[28:29], v[194:195], v[190:191]
	v_pk_fma_f32 v[30:31], v[30:31], v[196:197], v[192:193]
	v_cvt_pk_bf16_f32 v28, v28, v29
	v_cvt_pk_bf16_f32 v29, v30, v31
	global_store_dwordx2 v[34:35], v[28:29], off offset:512
	s_waitcnt vmcnt(4)
	v_pk_add_f32 v[202:203], v[202:203], 1.0 op_sel_hi:[1,0]
	v_pk_add_f32 v[204:205], v[204:205], 1.0 op_sel_hi:[1,0]
	v_pk_fma_f32 v[24:25], v[24:25], v[202:203], v[198:199]
	v_pk_fma_f32 v[26:27], v[26:27], v[204:205], v[200:201]
	v_cvt_pk_bf16_f32 v24, v24, v25
	v_cvt_pk_bf16_f32 v25, v26, v27
	global_store_dwordx2 v[34:35], v[24:25], off offset:1024
	s_waitcnt vmcnt(3)
	v_pk_add_f32 v[210:211], v[210:211], 1.0 op_sel_hi:[1,0]
	v_pk_add_f32 v[212:213], v[212:213], 1.0 op_sel_hi:[1,0]
	v_pk_fma_f32 v[16:17], v[16:17], v[210:211], v[206:207]
	v_pk_fma_f32 v[18:19], v[18:19], v[212:213], v[208:209]
	v_cvt_pk_bf16_f32 v16, v16, v17
	s_nop 0
	v_cvt_pk_bf16_f32 v17, v18, v19
	global_store_dwordx2 v[34:35], v[16:17], off offset:1536
	s_or_b64 exec, exec, s[10:11]
	s_and_saveexec_b64 s[10:11], s[38:39]
	s_cbranch_execz .LBB0_709
.LBB0_751:
	s_waitcnt lgkmcnt(0)
	v_add_f32_e32 v16, v73, v85
	v_fmamk_f32 v16, v16, 0x3a800000, v178
	v_cmp_gt_f32_e32 vcc, s34, v16
	v_mul_f32_e32 v17, 0x4b800000, v16
	v_add_u32_e32 v18, 8, v86
	v_cndmask_b32_e32 v16, v16, v17, vcc
	v_rsq_f32_e32 v16, v16
	s_mov_b32 s12, 0x18000
	v_mov_b32_e32 v83, v2
	v_ashrrev_i32_e32 v85, 31, v84
	v_mul_f32_e32 v17, 0x45800000, v16
	v_cndmask_b32_e32 v16, v16, v17, vcc
	v_cmp_gt_i32_e32 vcc, s29, v84
	v_ashrrev_i32_e32 v17, 11, v84
	v_lshlrev_b64 v[36:37], 11, v[84:85]
	v_cndmask_b32_e32 v17, v18, v17, vcc
	v_mov_b64_e32 v[18:19], s[8:9]
	v_mad_i64_i32 v[18:19], s[12:13], v17, s12, v[18:19]
	s_mov_b64 s[12:13], 0x1000
	s_nop 0
	v_lshl_add_u64 v[24:25], v[18:19], 0, s[12:13]
	v_lshl_add_u64 v[26:27], v[18:19], 0, v[82:83]
	v_lshl_add_u64 v[18:19], v[24:25], 0, v[82:83]
	global_load_dwordx4 v[28:31], v[26:27], off
	v_mov_b64_e32 v[214:215], v[18:19]
	global_load_dwordx4 v[32:35], v[18:19], off
	global_load_dwordx4 v[190:193], v[26:27], off offset:1024
	global_load_dwordx4 v[194:197], v[214:215], off offset:1024
	global_load_dwordx4 v[198:201], v[26:27], off offset:2048
	global_load_dwordx4 v[202:205], v[214:215], off offset:2048
	global_load_dwordx4 v[206:209], v[26:27], off offset:3072
	global_load_dwordx4 v[210:213], v[214:215], off offset:3072
	v_pk_mul_f32 v[18:19], v[20:21], v[16:17] op_sel_hi:[1,0]
	v_pk_mul_f32 v[20:21], v[22:23], v[16:17] op_sel_hi:[1,0]
	v_mov_b32_e32 v77, v2
	v_pk_mul_f32 v[12:13], v[12:13], v[16:17] op_sel_hi:[1,0]
	v_pk_mul_f32 v[14:15], v[14:15], v[16:17] op_sel_hi:[1,0]
	v_mov_b32_e32 v79, v2
	v_pk_mul_f32 v[8:9], v[8:9], v[16:17] op_sel_hi:[1,0]
	v_pk_mul_f32 v[10:11], v[10:11], v[16:17] op_sel_hi:[1,0]
	v_mov_b32_e32 v81, v2
	v_pk_mul_f32 v[4:5], v[4:5], v[16:17] op_sel_hi:[1,0]
	v_pk_mul_f32 v[6:7], v[6:7], v[16:17] op_sel_hi:[1,0]
	s_waitcnt vmcnt(6)
	v_pk_add_f32 v[32:33], v[32:33], 1.0 op_sel_hi:[1,0]
	v_pk_add_f32 v[22:23], v[34:35], 1.0 op_sel_hi:[1,0]
	v_pk_fma_f32 v[18:19], v[18:19], v[32:33], v[28:29]
	v_pk_fma_f32 v[20:21], v[20:21], v[22:23], v[30:31]
	v_cvt_pk_bf16_f32 v22, v18, v19
	v_lshl_add_u64 v[18:19], v[70:71], 0, v[36:37]
	v_cvt_pk_bf16_f32 v23, v20, v21
	global_store_dwordx2 v[18:19], v[22:23], off
	s_waitcnt vmcnt(5)
	v_pk_add_f32 v[194:195], v[194:195], 1.0 op_sel_hi:[1,0]
	v_pk_add_f32 v[196:197], v[196:197], 1.0 op_sel_hi:[1,0]
	v_pk_fma_f32 v[12:13], v[12:13], v[194:195], v[190:191]
	v_pk_fma_f32 v[14:15], v[14:15], v[196:197], v[192:193]
	v_cvt_pk_bf16_f32 v12, v12, v13
	v_cvt_pk_bf16_f32 v13, v14, v15
	global_store_dwordx2 v[18:19], v[12:13], off offset:512
	s_waitcnt vmcnt(4)
	v_pk_add_f32 v[202:203], v[202:203], 1.0 op_sel_hi:[1,0]
	v_pk_add_f32 v[204:205], v[204:205], 1.0 op_sel_hi:[1,0]
	v_pk_fma_f32 v[8:9], v[8:9], v[202:203], v[198:199]
	v_pk_fma_f32 v[10:11], v[10:11], v[204:205], v[200:201]
	v_cvt_pk_bf16_f32 v8, v8, v9
	v_cvt_pk_bf16_f32 v9, v10, v11
	global_store_dwordx2 v[18:19], v[8:9], off offset:1024
	s_waitcnt vmcnt(3)
	v_pk_add_f32 v[210:211], v[210:211], 1.0 op_sel_hi:[1,0]
	v_pk_add_f32 v[212:213], v[212:213], 1.0 op_sel_hi:[1,0]
	v_pk_fma_f32 v[4:5], v[4:5], v[210:211], v[206:207]
	v_pk_fma_f32 v[6:7], v[6:7], v[212:213], v[208:209]
	v_cvt_pk_bf16_f32 v4, v4, v5
	s_nop 0
	v_cvt_pk_bf16_f32 v5, v6, v7
	global_store_dwordx2 v[18:19], v[4:5], off offset:1536
	s_branch .LBB0_709
